# FF1 unit boundary: unit-top vmcnt(0)->vmcnt(16) and first two K-loop waits vmcnt(24) so epilogue stores drain under the next unit's first MFMA blocks
# speedup vs baseline: 1.0040x; 1.0040x over previous
.LBB13_1069:
	s_waitcnt vmcnt(16)
	v_add_f32_e32 v14, v4, v5
	v_add_f32_e32 v15, v6, v7
	v_add_f32_e32 v14, v14, v15
	v_add_f32_e32 v15, v0, v1
	v_add_f32_e32 v16, v2, v3
	v_add_f32_e32 v15, v15, v16
	v_add_f32_e32 v14, v14, v15
	ds_swizzle_b32 v15, v14 offset:swizzle(SWAP,1)
	s_and_saveexec_b64 s[22:23], s[6:7]
	s_cbranch_execz .LBB13_1071
	s_waitcnt lgkmcnt(0)
	v_add_f32_e32 v14, v14, v15
	v_fmamk_f32 v14, v14, 0x3a800000, v170
	v_mul_f32_e32 v15, 0x4b800000, v14
	v_cmp_gt_f32_e32 vcc, s52, v14
	s_lshl_b32 s19, s56, 11
	s_and_b32 s19, s19, 0x800
	v_cndmask_b32_e32 v14, v14, v15, vcc
	v_rsq_f32_e32 v14, v14
	s_nop 0
	v_mul_f32_e32 v15, 0x45800000, v14
	v_cndmask_b32_e32 v14, v14, v15, vcc
	v_add_u32_e32 v15, s19, v159
	ds_write_b32 v15, v14

;     __device__ float mid(int row) const { return rg(row) / ra(row); }
; #define PG8_STAGE(bufoff, gbase, voff) do { const char* gb_ = (const char*)(gbase); asm volatile("" : "+s"(gb_));     \
;         _Pragma("unroll") for (int _i = 0; _i < 2; ++_i) \
;         __builtin_amdgcn_global_load_lds((const unsigned*)(gb_ + (voff)[_i]), (PG8_LAS unsigned*)(lds + (bufoff) + ldsw + _i * 8192), 16, 0, 0); } while (0)
; #define PG8_LDA(dst, b, h) do { _Pragma("unroll") for (int m = 0; m < 4; ++m) _Pragma("unroll") for (int k = 0; k < 2; ++k) dst[m][k] = *(const PG8_LAS bf16x8*)(lds + PG8_SA(b, h) + aoff + m * 2048 + k * 1024); } while (0)
; #define PG8_LDB(dst, b, h) do { _Pragma("unroll") for (int n = 0; n < 2; ++n) _Pragma("unroll") for (int k = 0; k < 2; ++k) dst[n][k] = *(const PG8_LAS bf16x8*)(lds + PG8_SB(b, h) + boff + n * 2048 + k * 1024); } while (0)
; #define PG8_WAIT_V(n) asm volatile("s_waitcnt vmcnt(" #n ")" ::: "memory")
; #define PG8_WAIT_L(n) asm volatile("s_waitcnt lgkmcnt(" #n ")" ::: "memory")
; #define PG8_BAR __builtin_amdgcn_s_barrier()
; template <class Epi, class Sched, bool ALIGN_EPI = false, bool SP2 = false>
; __device__ __forceinline__ void gemm_phase(PG8_LAS unsigned char* lds, const Gemm g, const Sched& S, const Epi& E, int wid0) {
;     ...
;         for (int t = 0; t < nt; t += 2) {
;             const bool last = (t == nt - 2);
;             const char* a1 = cA + (size_t)(t + 1) * kstep;
;             const char* a2 = last ? nA : cA + (size_t)(t + 2) * kstep; const char* b2 = last ? nB : cB + (size_t)(t + 2) * kstep;
;             const char* a3 = a2 + kstep; const char* b3 = b2 + kstep;
;             if (last && has_next) S.a_ready(nxt);
;             if constexpr (Epi::HAS_MID) { if (t == Epi::MID_T) E.mid(acc, cur, wr, fr); }
;             unsigned vA_[2] = {voffA[0], voffA[1]}, vB_[2] = {voffB[0], voffB[1]};
;             asm volatile("" : "+v"(vA_[0]), "+v"(vA_[1]), "+v"(vB_[0]), "+v"(vB_[1]));
;             if constexpr (SP2) {
;             PG8_LDB(B0, 0, 0); PG8_LDB(B1, 0, 1); PG8_SCHED; PG8_LDA(At, 0, 0); PG8_STAGE(PG8_SA(1, 1), a1 + hstepA, vA_);
;             PG8_WAIT_V(8); PG8_WAIT_L(0); PG8_BAR; PG8_MMA(0, 0, At, B0); PG8_MMA(0, 1, At, B1); PG8_BAR; PG8_SCHED;
;             PG8_LDA(At, 0, 1); PG8_STAGE(PG8_SB(0, 0), b2, vB_); PG8_STAGE(PG8_SB(0, 1), b2 + hstep, vB_); PG8_STAGE(PG8_SA(0, 0), a2, vA_);
.LBB13_1074:
	v_mov_b32_e32 v218, v158
	v_mov_b32_e32 v219, v8
	v_mov_b32_e32 v220, v160
	v_mov_b32_e32 v221, v162
	ds_read_b128 v[142:145], v171
	ds_read_b128 v[146:149], v171 offset:1024
	ds_read_b128 v[150:153], v171 offset:2048
	ds_read_b128 v[154:157], v171 offset:3072
	ds_read_b128 v[164:167], v172
	ds_read_b128 v[174:177], v172 offset:1024
	ds_read_b128 v[178:181], v172 offset:2048
	ds_read_b128 v[182:185], v172 offset:3072
	s_add_u32 s34, s8, 0x100
	s_addc_u32 s35, s9, 0
	s_cmp_eq_u32 s61, 12
	s_cselect_b32 s40, s57, s34
	s_cselect_b32 s41, s19, s35
	s_cselect_b32 s38, s58, s59
	s_cselect_b32 s39, s21, s60
	s_add_u32 s36, s40, 0x80
	s_addc_u32 s37, s41, 0
	s_add_u32 s8, s8, 0x40080
	s_addc_u32 s9, s9, 0
	s_add_i32 m0, s29, 0xc000
	ds_read_b128 v[186:189], v173
	ds_read_b128 v[190:193], v173 offset:1024
	ds_read_b128 v[194:197], v173 offset:2048
	ds_read_b128 v[198:201], v173 offset:3072
	ds_read_b128 v[202:205], v173 offset:4096
	ds_read_b128 v[206:209], v173 offset:5120
	ds_read_b128 v[210:213], v173 offset:6144
	ds_read_b128 v[214:217], v173 offset:7168
	s_nop 0
	global_load_lds_dwordx4 v218, s[8:9]
	s_add_i32 m0, s29, 0xe000
	s_nop 0
	global_load_lds_dwordx4 v220, s[8:9]
	s_cmp_lg_u32 s61, -2
	s_cbranch_scc1 .Lff1a_w8_0
	s_cmp_eq_u32 s56, 0
	s_cbranch_scc1 .Lff1a_w8_0
	s_waitcnt vmcnt(24)
	s_branch .Lff1a_wd_0
.Lff1a_w8_0:
	s_waitcnt vmcnt(8)
.Lff1a_wd_0:
	s_waitcnt lgkmcnt(0)
	s_barrier
	s_setprio 1
	s_waitcnt lgkmcnt(0)
	v_mfma_f32_16x16x32_bf16 v[138:141], v[142:145], v[186:189], v[138:141]
	v_mfma_f32_16x16x32_bf16 v[134:137], v[150:153], v[186:189], v[134:137]
	v_mfma_f32_16x16x32_bf16 v[122:125], v[142:145], v[194:197], v[122:125]
	v_mfma_f32_16x16x32_bf16 v[118:121], v[150:153], v[194:197], v[118:121]
	v_mfma_f32_16x16x32_bf16 v[106:109], v[142:145], v[202:205], v[106:109]
	v_mfma_f32_16x16x32_bf16 v[102:105], v[150:153], v[202:205], v[102:105]
	v_mfma_f32_16x16x32_bf16 v[90:93], v[142:145], v[210:213], v[90:93]
	v_mfma_f32_16x16x32_bf16 v[86:89], v[150:153], v[210:213], v[86:89]
	v_mfma_f32_16x16x32_bf16 v[138:141], v[146:149], v[190:193], v[138:141]
	v_mfma_f32_16x16x32_bf16 v[134:137], v[154:157], v[190:193], v[134:137]
	v_mfma_f32_16x16x32_bf16 v[122:125], v[146:149], v[198:201], v[122:125]
	v_mfma_f32_16x16x32_bf16 v[118:121], v[154:157], v[198:201], v[118:121]
	v_mfma_f32_16x16x32_bf16 v[106:109], v[146:149], v[206:209], v[106:109]
	v_mfma_f32_16x16x32_bf16 v[102:105], v[154:157], v[206:209], v[102:105]
	v_mfma_f32_16x16x32_bf16 v[90:93], v[146:149], v[214:217], v[90:93]
	v_mfma_f32_16x16x32_bf16 v[86:89], v[154:157], v[214:217], v[86:89]
	s_setprio 0
	s_setprio 1
	v_mfma_f32_16x16x32_bf16 v[130:133], v[164:167], v[186:189], v[130:133]
	v_mfma_f32_16x16x32_bf16 v[126:129], v[178:181], v[186:189], v[126:129]
	v_mfma_f32_16x16x32_bf16 v[114:117], v[164:167], v[194:197], v[114:117]
	v_mfma_f32_16x16x32_bf16 v[110:113], v[178:181], v[194:197], v[110:113]
	v_mfma_f32_16x16x32_bf16 v[98:101], v[164:167], v[202:205], v[98:101]
	v_mfma_f32_16x16x32_bf16 v[94:97], v[178:181], v[202:205], v[94:97]
	v_mfma_f32_16x16x32_bf16 v[82:85], v[164:167], v[210:213], v[82:85]
	v_mfma_f32_16x16x32_bf16 v[78:81], v[178:181], v[210:213], v[78:81]
	v_mfma_f32_16x16x32_bf16 v[130:133], v[174:177], v[190:193], v[130:133]
	v_mfma_f32_16x16x32_bf16 v[126:129], v[182:185], v[190:193], v[126:129]
	v_mfma_f32_16x16x32_bf16 v[114:117], v[174:177], v[198:201], v[114:117]
	v_mfma_f32_16x16x32_bf16 v[110:113], v[182:185], v[198:201], v[110:113]
	v_mfma_f32_16x16x32_bf16 v[98:101], v[174:177], v[206:209], v[98:101]
	v_mfma_f32_16x16x32_bf16 v[94:97], v[182:185], v[206:209], v[94:97]
	v_mfma_f32_16x16x32_bf16 v[82:85], v[174:177], v[214:217], v[82:85]
	v_mfma_f32_16x16x32_bf16 v[78:81], v[182:185], v[214:217], v[78:81]
	s_setprio 0
	s_barrier
	s_add_i32 s62, s53, s27
	s_mov_b64 s[8:9], s[38:39]
	s_mov_b32 m0, s62
	ds_read_b128 v[186:189], v173 offset:16384
	ds_read_b128 v[190:193], v173 offset:17408
	ds_read_b128 v[194:197], v173 offset:18432
	ds_read_b128 v[198:201], v173 offset:19456
	ds_read_b128 v[202:205], v173 offset:20480
	ds_read_b128 v[206:209], v173 offset:21504
	ds_read_b128 v[210:213], v173 offset:22528
	ds_read_b128 v[214:217], v173 offset:23552
	s_nop 0
	global_load_lds_dwordx4 v219, s[8:9]
	s_add_i32 m0, s62, 0x2000
	s_nop 0
	global_load_lds_dwordx4 v221, s[8:9]
	s_add_u32 s8, s38, 0x40000
	s_addc_u32 s9, s39, 0
	s_add_i32 s62, s54, s27
	s_mov_b32 m0, s62
	s_nop 0
	global_load_lds_dwordx4 v219, s[8:9]
	s_add_i32 m0, s62, 0x2000
	s_nop 0
	global_load_lds_dwordx4 v221, s[8:9]
	s_mov_b64 s[8:9], s[40:41]
	s_mov_b32 m0, s29
	s_nop 0
	global_load_lds_dwordx4 v218, s[8:9]
	s_mov_b32 m0, s45
	s_nop 0
	global_load_lds_dwordx4 v220, s[8:9]
	s_cmp_lg_u32 s61, -2
	s_cbranch_scc1 .Lff1a_w8_1
	s_cmp_eq_u32 s56, 0
	s_cbranch_scc1 .Lff1a_w8_1
	s_waitcnt vmcnt(24)
	s_branch .Lff1a_wd_1

; #define PG8_STAGE(bufoff, gbase, voff) do { const char* gb_ = (const char*)(gbase); asm volatile("" : "+s"(gb_));     \
;         _Pragma("unroll") for (int _i = 0; _i < 2; ++_i) \
;         __builtin_amdgcn_global_load_lds((const unsigned*)(gb_ + (voff)[_i]), (PG8_LAS unsigned*)(lds + (bufoff) + ldsw + _i * 8192), 16, 0, 0); } while (0)
; #define PG8_LDA(dst, b, h) do { _Pragma("unroll") for (int m = 0; m < 4; ++m) _Pragma("unroll") for (int k = 0; k < 2; ++k) dst[m][k] = *(const PG8_LAS bf16x8*)(lds + PG8_SA(b, h) + aoff + m * 2048 + k * 1024); } while (0)
; #define PG8_LDB(dst, b, h) do { _Pragma("unroll") for (int n = 0; n < 2; ++n) _Pragma("unroll") for (int k = 0; k < 2; ++k) dst[n][k] = *(const PG8_LAS bf16x8*)(lds + PG8_SB(b, h) + boff + n * 2048 + k * 1024); } while (0)
; #define PG8_MMA(ai, bj, At, Bt) do { __builtin_amdgcn_s_setprio(1); _Pragma("unroll") for (int m = 0; m < 4; ++m) _Pragma("unroll") for (int n = 0; n < 2; ++n) _Pragma("unroll") for (int k = 0; k < 2; ++k) \
;         acc[ai][bj][m][n] = __builtin_amdgcn_mfma_f32_16x16x32_bf16(Bt[n][k], At[m][k], acc[ai][bj][m][n], 0, 0, 0); __builtin_amdgcn_s_setprio(0); } while (0)
; #define PG8_WAIT_V(n) asm volatile("s_waitcnt vmcnt(" #n ")" ::: "memory")
; #define PG8_WAIT_L(n) asm volatile("s_waitcnt lgkmcnt(" #n ")" ::: "memory")
; #define PG8_BAR __builtin_amdgcn_s_barrier()
; #define PG8_SCHED __builtin_amdgcn_sched_barrier(0)
; template <class Epi, class Sched, bool ALIGN_EPI = false, bool SP2 = false>
; __device__ __forceinline__ void gemm_phase(PG8_LAS unsigned char* lds, const Gemm g, const Sched& S, const Epi& E, int wid0) {
;     ...
;             PG8_LDB(B0, 0, 0); PG8_LDB(B1, 0, 1); PG8_SCHED; PG8_LDA(At, 0, 0); PG8_STAGE(PG8_SA(1, 1), a1 + hstepA, vA_);
;             PG8_WAIT_V(8); PG8_WAIT_L(0); PG8_BAR; PG8_MMA(0, 0, At, B0); PG8_MMA(0, 1, At, B1); PG8_BAR; PG8_SCHED;
;             PG8_LDA(At, 0, 1); PG8_STAGE(PG8_SB(0, 0), b2, vB_); PG8_STAGE(PG8_SB(0, 1), b2 + hstep, vB_); PG8_STAGE(PG8_SA(0, 0), a2, vA_);
;             PG8_WAIT_V(8); PG8_WAIT_L(0); PG8_BAR; PG8_MMA(1, 0, At, B0); PG8_MMA(1, 1, At, B1); PG8_BAR; PG8_SCHED;
;             PG8_LDB(B0, 1, 0); PG8_LDB(B1, 1, 1); PG8_SCHED; PG8_LDA(At, 1, 0); PG8_STAGE(PG8_SA(0, 1), a2 + hstepA, vA_);
;             PG8_WAIT_V(8); PG8_WAIT_L(0); PG8_BAR; PG8_MMA(0, 0, At, B0); PG8_MMA(0, 1, At, B1); PG8_BAR; PG8_SCHED;
.Lff1a_wd_1:
	s_waitcnt lgkmcnt(0)
	s_barrier
	s_setprio 1
	s_waitcnt lgkmcnt(0)
	v_mfma_f32_16x16x32_bf16 v[74:77], v[142:145], v[186:189], v[74:77]
	v_mfma_f32_16x16x32_bf16 v[70:73], v[150:153], v[186:189], v[70:73]
	v_mfma_f32_16x16x32_bf16 v[58:61], v[142:145], v[194:197], v[58:61]
	v_mfma_f32_16x16x32_bf16 v[54:57], v[150:153], v[194:197], v[54:57]
	v_mfma_f32_16x16x32_bf16 v[42:45], v[142:145], v[202:205], v[42:45]
	v_mfma_f32_16x16x32_bf16 v[38:41], v[150:153], v[202:205], v[38:41]
	v_mfma_f32_16x16x32_bf16 v[26:29], v[142:145], v[210:213], v[26:29]
	v_mfma_f32_16x16x32_bf16 v[22:25], v[150:153], v[210:213], v[22:25]
	v_mfma_f32_16x16x32_bf16 v[74:77], v[146:149], v[190:193], v[74:77]
	v_mfma_f32_16x16x32_bf16 v[70:73], v[154:157], v[190:193], v[70:73]
	v_mfma_f32_16x16x32_bf16 v[58:61], v[146:149], v[198:201], v[58:61]
	v_mfma_f32_16x16x32_bf16 v[54:57], v[154:157], v[198:201], v[54:57]
	v_mfma_f32_16x16x32_bf16 v[42:45], v[146:149], v[206:209], v[42:45]
	v_mfma_f32_16x16x32_bf16 v[38:41], v[154:157], v[206:209], v[38:41]
	v_mfma_f32_16x16x32_bf16 v[26:29], v[146:149], v[214:217], v[26:29]
	v_mfma_f32_16x16x32_bf16 v[22:25], v[154:157], v[214:217], v[22:25]
	s_setprio 0
	s_setprio 1
	v_mfma_f32_16x16x32_bf16 v[66:69], v[164:167], v[186:189], v[66:69]
	v_mfma_f32_16x16x32_bf16 v[62:65], v[178:181], v[186:189], v[62:65]
	v_mfma_f32_16x16x32_bf16 v[50:53], v[164:167], v[194:197], v[50:53]
	v_mfma_f32_16x16x32_bf16 v[46:49], v[178:181], v[194:197], v[46:49]
	v_mfma_f32_16x16x32_bf16 v[34:37], v[164:167], v[202:205], v[34:37]
	v_mfma_f32_16x16x32_bf16 v[30:33], v[178:181], v[202:205], v[30:33]
	v_mfma_f32_16x16x32_bf16 v[18:21], v[164:167], v[210:213], v[18:21]
	v_mfma_f32_16x16x32_bf16 v[14:17], v[178:181], v[210:213], v[14:17]
	v_mfma_f32_16x16x32_bf16 v[66:69], v[174:177], v[190:193], v[66:69]
	v_mfma_f32_16x16x32_bf16 v[62:65], v[182:185], v[190:193], v[62:65]
	v_mfma_f32_16x16x32_bf16 v[50:53], v[174:177], v[198:201], v[50:53]
	v_mfma_f32_16x16x32_bf16 v[46:49], v[182:185], v[198:201], v[46:49]
	v_mfma_f32_16x16x32_bf16 v[34:37], v[174:177], v[206:209], v[34:37]
	v_mfma_f32_16x16x32_bf16 v[30:33], v[182:185], v[206:209], v[30:33]
	v_mfma_f32_16x16x32_bf16 v[18:21], v[174:177], v[214:217], v[18:21]
	v_mfma_f32_16x16x32_bf16 v[14:17], v[182:185], v[214:217], v[14:17]
	s_setprio 0
	s_barrier
	s_add_i32 s62, 0, 0x18000
	s_add_i32 s63, 0, 0x1c000
	v_add_u32_e32 v154, s62, v9
	v_add_u32_e32 v182, s63, v9
	ds_read_b128 v[142:145], v154
	ds_read_b128 v[146:149], v154 offset:1024
	ds_read_b128 v[150:153], v154 offset:2048
	ds_read_b128 v[154:157], v154 offset:3072
	ds_read_b128 v[164:167], v182
	ds_read_b128 v[174:177], v182 offset:1024
	ds_read_b128 v[178:181], v182 offset:2048
	ds_read_b128 v[182:185], v182 offset:3072
	s_add_u32 s8, s40, 0x40000
	s_addc_u32 s9, s41, 0
	s_mov_b32 m0, s46
	ds_read_b128 v[186:189], v173 offset:32768
	ds_read_b128 v[190:193], v173 offset:33792
	ds_read_b128 v[194:197], v173 offset:34816
	ds_read_b128 v[198:201], v173 offset:35840
	ds_read_b128 v[202:205], v173 offset:36864
	ds_read_b128 v[206:209], v173 offset:37888
	ds_read_b128 v[210:213], v173 offset:38912
	ds_read_b128 v[214:217], v173 offset:39936
	s_nop 0
	global_load_lds_dwordx4 v218, s[8:9]
	s_mov_b32 m0, s47
	s_nop 0
	global_load_lds_dwordx4 v220, s[8:9]
	s_waitcnt vmcnt(8)
	s_waitcnt lgkmcnt(0)
	s_barrier
	s_setprio 1
	s_waitcnt lgkmcnt(0)
	v_mfma_f32_16x16x32_bf16 v[138:141], v[142:145], v[186:189], v[138:141]
	v_mfma_f32_16x16x32_bf16 v[134:137], v[150:153], v[186:189], v[134:137]
	v_mfma_f32_16x16x32_bf16 v[122:125], v[142:145], v[194:197], v[122:125]
	v_mfma_f32_16x16x32_bf16 v[118:121], v[150:153], v[194:197], v[118:121]
	v_mfma_f32_16x16x32_bf16 v[106:109], v[142:145], v[202:205], v[106:109]
	v_mfma_f32_16x16x32_bf16 v[102:105], v[150:153], v[202:205], v[102:105]
	v_mfma_f32_16x16x32_bf16 v[90:93], v[142:145], v[210:213], v[90:93]
	v_mfma_f32_16x16x32_bf16 v[86:89], v[150:153], v[210:213], v[86:89]
	v_mfma_f32_16x16x32_bf16 v[138:141], v[146:149], v[190:193], v[138:141]
	v_mfma_f32_16x16x32_bf16 v[134:137], v[154:157], v[190:193], v[134:137]
	v_mfma_f32_16x16x32_bf16 v[122:125], v[146:149], v[198:201], v[122:125]
	v_mfma_f32_16x16x32_bf16 v[118:121], v[154:157], v[198:201], v[118:121]
	v_mfma_f32_16x16x32_bf16 v[106:109], v[146:149], v[206:209], v[106:109]
	v_mfma_f32_16x16x32_bf16 v[102:105], v[154:157], v[206:209], v[102:105]
	v_mfma_f32_16x16x32_bf16 v[90:93], v[146:149], v[214:217], v[90:93]
	v_mfma_f32_16x16x32_bf16 v[86:89], v[154:157], v[214:217], v[86:89]
	s_setprio 0
	s_setprio 1
	v_mfma_f32_16x16x32_bf16 v[130:133], v[164:167], v[186:189], v[130:133]
	v_mfma_f32_16x16x32_bf16 v[126:129], v[178:181], v[186:189], v[126:129]
	v_mfma_f32_16x16x32_bf16 v[114:117], v[164:167], v[194:197], v[114:117]
	v_mfma_f32_16x16x32_bf16 v[110:113], v[178:181], v[194:197], v[110:113]
	v_mfma_f32_16x16x32_bf16 v[98:101], v[164:167], v[202:205], v[98:101]
	v_mfma_f32_16x16x32_bf16 v[94:97], v[178:181], v[202:205], v[94:97]
	v_mfma_f32_16x16x32_bf16 v[82:85], v[164:167], v[210:213], v[82:85]
	v_mfma_f32_16x16x32_bf16 v[78:81], v[178:181], v[210:213], v[78:81]
	v_mfma_f32_16x16x32_bf16 v[130:133], v[174:177], v[190:193], v[130:133]
	v_mfma_f32_16x16x32_bf16 v[126:129], v[182:185], v[190:193], v[126:129]
	v_mfma_f32_16x16x32_bf16 v[114:117], v[174:177], v[198:201], v[114:117]
	v_mfma_f32_16x16x32_bf16 v[110:113], v[182:185], v[198:201], v[110:113]
	v_mfma_f32_16x16x32_bf16 v[98:101], v[174:177], v[206:209], v[98:101]
	v_mfma_f32_16x16x32_bf16 v[94:97], v[182:185], v[206:209], v[94:97]
	v_mfma_f32_16x16x32_bf16 v[82:85], v[174:177], v[214:217], v[82:85]
	v_mfma_f32_16x16x32_bf16 v[78:81], v[182:185], v[214:217], v[78:81]
	s_setprio 0
	s_barrier
; #define PG8_STAGE(bufoff, gbase, voff) do { const char* gb_ = (const char*)(gbase); asm volatile("" : "+s"(gb_));     \
;         _Pragma("unroll") for (int _i = 0; _i < 2; ++_i) \
;         __builtin_amdgcn_global_load_lds((const unsigned*)(gb_ + (voff)[_i]), (PG8_LAS unsigned*)(lds + (bufoff) + ldsw + _i * 8192), 16, 0, 0); } while (0)
; #define PG8_LDA(dst, b, h) do { _Pragma("unroll") for (int m = 0; m < 4; ++m) _Pragma("unroll") for (int k = 0; k < 2; ++k) dst[m][k] = *(const PG8_LAS bf16x8*)(lds + PG8_SA(b, h) + aoff + m * 2048 + k * 1024); } while (0)
; #define PG8_MMA(ai, bj, At, Bt) do { __builtin_amdgcn_s_setprio(1); _Pragma("unroll") for (int m = 0; m < 4; ++m) _Pragma("unroll") for (int n = 0; n < 2; ++n) _Pragma("unroll") for (int k = 0; k < 2; ++k) \
;         acc[ai][bj][m][n] = __builtin_amdgcn_mfma_f32_16x16x32_bf16(Bt[n][k], At[m][k], acc[ai][bj][m][n], 0, 0, 0); __builtin_amdgcn_s_setprio(0); } while (0)
; #define PG8_WAIT_V(n) asm volatile("s_waitcnt vmcnt(" #n ")" ::: "memory")
; #define PG8_WAIT_L(n) asm volatile("s_waitcnt lgkmcnt(" #n ")" ::: "memory")
; #define PG8_BAR __builtin_amdgcn_s_barrier()
; #define PG8_SCHED __builtin_amdgcn_sched_barrier(0)
; template <class Epi, class Sched, bool ALIGN_EPI = false, bool SP2 = false>
; __device__ __forceinline__ void gemm_phase(PG8_LAS unsigned char* lds, const Gemm g, const Sched& S, const Epi& E, int wid0) {
;     ...
;             PG8_LDA(At, 1, 1); PG8_STAGE(PG8_SB(1, 0), b3, vB_); PG8_STAGE(PG8_SB(1, 1), b3 + hstep, vB_); PG8_STAGE(PG8_SA(1, 0), a3, vA_);
;             PG8_WAIT_V(8); PG8_WAIT_L(0); PG8_BAR; PG8_MMA(1, 0, At, B0); PG8_MMA(1, 1, At, B1); PG8_BAR; PG8_SCHED;
	s_add_u32 s8, s38, 0x80
	s_addc_u32 s9, s39, 0
	s_add_i32 s40, s62, s27
	s_mov_b32 m0, s40
	ds_read_b128 v[186:189], v173 offset:49152
	ds_read_b128 v[190:193], v173 offset:50176
	ds_read_b128 v[194:197], v173 offset:51200
	ds_read_b128 v[198:201], v173 offset:52224
	ds_read_b128 v[202:205], v173 offset:53248
	ds_read_b128 v[206:209], v173 offset:54272
	ds_read_b128 v[210:213], v173 offset:55296
	ds_read_b128 v[214:217], v173 offset:56320
	s_nop 0
	global_load_lds_dwordx4 v219, s[8:9]
	s_add_i32 m0, s40, 0x2000
	s_nop 0
	global_load_lds_dwordx4 v221, s[8:9]
	s_add_u32 s8, s38, 0x40080
	s_addc_u32 s9, s39, 0
	s_add_i32 s38, s63, s27
	s_mov_b32 m0, s38
	s_nop 0
	global_load_lds_dwordx4 v219, s[8:9]
	s_add_i32 m0, s38, 0x2000
	s_nop 0
	global_load_lds_dwordx4 v221, s[8:9]
	s_mov_b32 m0, s50
	s_nop 0
	global_load_lds_dwordx4 v218, s[36:37]
	s_mov_b32 m0, s51
	s_nop 0
	global_load_lds_dwordx4 v220, s[36:37]
	s_waitcnt vmcnt(8)
	s_waitcnt lgkmcnt(0)
	s_barrier
	s_setprio 1
	s_waitcnt lgkmcnt(0)
	v_mfma_f32_16x16x32_bf16 v[74:77], v[142:145], v[186:189], v[74:77]
	v_mfma_f32_16x16x32_bf16 v[70:73], v[150:153], v[186:189], v[70:73]
	v_mfma_f32_16x16x32_bf16 v[58:61], v[142:145], v[194:197], v[58:61]
	v_mfma_f32_16x16x32_bf16 v[54:57], v[150:153], v[194:197], v[54:57]
	v_mfma_f32_16x16x32_bf16 v[42:45], v[142:145], v[202:205], v[42:45]
	v_mfma_f32_16x16x32_bf16 v[38:41], v[150:153], v[202:205], v[38:41]
	v_mfma_f32_16x16x32_bf16 v[26:29], v[142:145], v[210:213], v[26:29]
	v_mfma_f32_16x16x32_bf16 v[22:25], v[150:153], v[210:213], v[22:25]
	v_mfma_f32_16x16x32_bf16 v[74:77], v[146:149], v[190:193], v[74:77]
	v_mfma_f32_16x16x32_bf16 v[70:73], v[154:157], v[190:193], v[70:73]
	v_mfma_f32_16x16x32_bf16 v[58:61], v[146:149], v[198:201], v[58:61]
	v_mfma_f32_16x16x32_bf16 v[54:57], v[154:157], v[198:201], v[54:57]
	v_mfma_f32_16x16x32_bf16 v[42:45], v[146:149], v[206:209], v[42:45]
	v_mfma_f32_16x16x32_bf16 v[38:41], v[154:157], v[206:209], v[38:41]
	v_mfma_f32_16x16x32_bf16 v[26:29], v[146:149], v[214:217], v[26:29]
	v_mfma_f32_16x16x32_bf16 v[22:25], v[154:157], v[214:217], v[22:25]
	s_setprio 0
	s_setprio 1
	v_mfma_f32_16x16x32_bf16 v[66:69], v[164:167], v[186:189], v[66:69]
	v_mfma_f32_16x16x32_bf16 v[62:65], v[178:181], v[186:189], v[62:65]
	v_mfma_f32_16x16x32_bf16 v[50:53], v[164:167], v[194:197], v[50:53]
	v_mfma_f32_16x16x32_bf16 v[46:49], v[178:181], v[194:197], v[46:49]
	v_mfma_f32_16x16x32_bf16 v[34:37], v[164:167], v[202:205], v[34:37]
	v_mfma_f32_16x16x32_bf16 v[30:33], v[178:181], v[202:205], v[30:33]
	v_mfma_f32_16x16x32_bf16 v[18:21], v[164:167], v[210:213], v[18:21]
	v_mfma_f32_16x16x32_bf16 v[14:17], v[178:181], v[210:213], v[14:17]
	v_mfma_f32_16x16x32_bf16 v[66:69], v[174:177], v[190:193], v[66:69]
	v_mfma_f32_16x16x32_bf16 v[62:65], v[182:185], v[190:193], v[62:65]
	v_mfma_f32_16x16x32_bf16 v[50:53], v[174:177], v[198:201], v[50:53]
	v_mfma_f32_16x16x32_bf16 v[46:49], v[182:185], v[198:201], v[46:49]
	v_mfma_f32_16x16x32_bf16 v[34:37], v[174:177], v[206:209], v[34:37]
	v_mfma_f32_16x16x32_bf16 v[30:33], v[182:185], v[206:209], v[30:33]
	v_mfma_f32_16x16x32_bf16 v[18:21], v[174:177], v[214:217], v[18:21]
	v_mfma_f32_16x16x32_bf16 v[14:17], v[182:185], v[214:217], v[14:17]
	s_setprio 0
	s_barrier
	s_add_i32 s61, s61, 2
	s_add_u32 s59, s59, 0x100
	s_addc_u32 s60, s60, 0
	s_cmp_gt_u32 s61, 13
	s_mov_b64 s[8:9], s[34:35]
	s_cbranch_scc0 .LBB13_1074
	s_and_b64 vcc, exec, s[16:17]
	s_cbranch_vccz .LBB13_1077
	s_barrier
